# exps pipelined into the P.V block; K/V LDS-DMA issue moved behind the V fragment reads
# speedup vs baseline: 1.0223x; 1.0043x over previous
.LBB0_280:
	s_waitcnt lgkmcnt(5)
	v_mfma_f32_32x32x16_bf16 v[66:81], v[166:169], v[134:137], v[66:81]
	s_waitcnt lgkmcnt(4)
	v_mfma_f32_32x32x16_bf16 v[82:97], v[162:165], v[134:137], v[82:97]
	s_waitcnt lgkmcnt(3)
	v_mfma_f32_32x32x16_bf16 v[66:81], v[158:161], v[138:141], v[66:81]
	s_waitcnt lgkmcnt(2)
	v_mfma_f32_32x32x16_bf16 v[82:97], v[154:157], v[138:141], v[82:97]
	s_waitcnt lgkmcnt(1)
	v_mfma_f32_32x32x16_bf16 v[66:81], v[150:153], v[142:145], v[66:81]
	s_waitcnt lgkmcnt(0)
	v_mfma_f32_32x32x16_bf16 v[82:97], v[146:149], v[142:145], v[82:97]
	v_pk_add_f32 v[146:147], v[114:115], v[98:99]
	v_pk_add_f32 v[148:149], v[116:117], v[100:101]
	v_pk_add_f32 v[150:151], v[118:119], v[102:103]
	v_pk_add_f32 v[152:153], v[120:121], v[104:105]
	v_pk_add_f32 v[154:155], v[122:123], v[106:107]
	v_pk_add_f32 v[156:157], v[124:125], v[108:109]
	v_pk_add_f32 v[158:159], v[126:127], v[110:111]
	v_pk_add_f32 v[160:161], v[128:129], v[112:113]
	v_pk_add_f32 v[146:147], v[146:147], v[148:149]
	v_pk_add_f32 v[150:151], v[150:151], v[152:153]
	v_pk_add_f32 v[154:155], v[154:155], v[156:157]
	v_pk_add_f32 v[158:159], v[158:159], v[160:161]
	v_pk_add_f32 v[146:147], v[146:147], v[150:151]
	v_pk_add_f32 v[154:155], v[154:155], v[158:159]
	v_cvt_pk_bf16_f32 v113, v112, v113
	v_cvt_pk_bf16_f32 v112, v110, v111
	v_cvt_pk_bf16_f32 v111, v108, v109
	v_cvt_pk_bf16_f32 v110, v106, v107
	v_pk_add_f32 v[146:147], v[146:147], v[154:155]
	v_cvt_pk_bf16_f32 v109, v104, v105
	v_cvt_pk_bf16_f32 v108, v102, v103
	v_cvt_pk_bf16_f32 v107, v100, v101
	v_cvt_pk_bf16_f32 v106, v98, v99
	v_cvt_pk_bf16_f32 v98, v114, v115
	v_cvt_pk_bf16_f32 v99, v116, v117
	v_cvt_pk_bf16_f32 v100, v118, v119
	v_cvt_pk_bf16_f32 v101, v120, v121
	v_cvt_pk_bf16_f32 v102, v122, v123
	v_cvt_pk_bf16_f32 v103, v124, v125
	v_cvt_pk_bf16_f32 v104, v126, v127
	v_cvt_pk_bf16_f32 v105, v128, v129
	v_add_f32_e32 v162, v146, v147
	s_nop 0
	v_add_f32_e32 v213, v162, v0
	ds_read_b128 v[114:117], v208 offset:49152
	ds_read_b128 v[118:121], v208 offset:53248
	ds_read_b128 v[122:125], v208 offset:57344
	ds_read_b128 v[126:129], v208 offset:61440
	ds_read_b128 v[150:153], v209 offset:53248
	ds_read_b128 v[146:149], v209 offset:49152
	ds_read_b128 v[154:157], v209 offset:57344
	ds_read_b128 v[158:161], v209 offset:61440
	s_and_b32 s0, s77, 0x3f0000
	s_lshl_b32 s22, s0, 1
	s_mov_b32 m0, s73
	v_lshl_add_u64 v[164:165], v[188:189], 0, s[22:23]
	global_load_lds_dwordx4 v[164:165], off
	v_lshl_add_u64 v[164:165], v[192:193], 0, s[22:23]
	s_mov_b32 m0, s31
	s_lshl_b32 s22, s15, 1
	global_load_lds_dwordx4 v[164:165], off
	v_lshl_add_u64 v[164:165], v[190:191], 0, s[22:23]
	s_mov_b32 m0, s71
	global_load_lds_dwordx4 v[164:165], off
	v_lshl_add_u64 v[164:165], v[194:195], 0, s[22:23]
	s_mov_b32 m0, s72
	s_nop 0
	global_load_lds_dwordx4 v[164:165], off
	s_waitcnt lgkmcnt(0)
	v_mfma_f32_32x32x16_bf16 v[50:65], v[98:101], v[114:117], v[50:65]
	ds_read_b128 v[114:117], v210 offset:53248
	v_exp_f32_e32 v66, v66
	v_exp_f32_e32 v67, v67
	v_mfma_f32_32x32x16_bf16 v[34:49], v[98:101], v[118:121], v[34:49]
	ds_read_b128 v[118:121], v210 offset:57344
	v_exp_f32_e32 v68, v68
	v_exp_f32_e32 v69, v69
	v_mfma_f32_32x32x16_bf16 v[18:33], v[98:101], v[122:125], v[18:33]
	ds_read_b128 v[122:125], v210 offset:61440
	v_exp_f32_e32 v70, v70
	v_exp_f32_e32 v71, v71
	v_mfma_f32_32x32x16_bf16 v[2:17], v[98:101], v[126:129], v[2:17]
	ds_read_b128 v[98:101], v210 offset:49152
	v_exp_f32_e32 v72, v72
	v_exp_f32_e32 v73, v73
	v_mfma_f32_32x32x16_bf16 v[50:65], v[102:105], v[146:149], v[50:65]
	ds_read_b128 v[126:129], v212 offset:53248
	v_exp_f32_e32 v74, v74
	v_exp_f32_e32 v75, v75
	v_mfma_f32_32x32x16_bf16 v[34:49], v[102:105], v[150:153], v[34:49]
	ds_read_b128 v[146:149], v212 offset:57344
	v_exp_f32_e32 v76, v76
	v_exp_f32_e32 v77, v77
	v_mfma_f32_32x32x16_bf16 v[18:33], v[102:105], v[154:157], v[18:33]
	ds_read_b128 v[150:153], v212 offset:61440
	v_exp_f32_e32 v78, v78
	v_exp_f32_e32 v79, v79
	v_mfma_f32_32x32x16_bf16 v[2:17], v[102:105], v[158:161], v[2:17]
	ds_read_b128 v[102:105], v212 offset:49152
	v_exp_f32_e32 v80, v80
	v_exp_f32_e32 v81, v81
	s_waitcnt lgkmcnt(0)
	v_mfma_f32_32x32x16_bf16 v[50:65], v[106:109], v[98:101], v[50:65]
	v_exp_f32_e32 v82, v82
	v_exp_f32_e32 v83, v83
	v_mfma_f32_32x32x16_bf16 v[34:49], v[106:109], v[114:117], v[34:49]
	v_exp_f32_e32 v84, v84
	v_exp_f32_e32 v85, v85
	v_mfma_f32_32x32x16_bf16 v[18:33], v[106:109], v[118:121], v[18:33]
	v_exp_f32_e32 v86, v86
	v_exp_f32_e32 v87, v87
	v_mfma_f32_32x32x16_bf16 v[2:17], v[106:109], v[122:125], v[2:17]
	v_exp_f32_e32 v88, v88
	v_exp_f32_e32 v89, v89
	v_mfma_f32_32x32x16_bf16 v[50:65], v[110:113], v[102:105], v[50:65]
	v_exp_f32_e32 v90, v90
	v_exp_f32_e32 v91, v91
	v_mfma_f32_32x32x16_bf16 v[34:49], v[110:113], v[126:129], v[34:49]
	v_exp_f32_e32 v92, v92
	v_exp_f32_e32 v93, v93
	v_mfma_f32_32x32x16_bf16 v[18:33], v[110:113], v[146:149], v[18:33]
	v_exp_f32_e32 v94, v94
	v_exp_f32_e32 v95, v95
	v_mfma_f32_32x32x16_bf16 v[2:17], v[110:113], v[150:153], v[2:17]
	v_exp_f32_e32 v96, v96
	v_exp_f32_e32 v97, v97
	s_waitcnt vmcnt(0)
	s_add_i32 s76, s76, 2
	s_add_i32 s77, s77, 0x20000
	s_cmp_gt_u32 s76, 61
	s_waitcnt vmcnt(0)
	s_barrier
	s_cbranch_scc1 .LBB0_295

.LBB0_288:
	s_waitcnt lgkmcnt(5)
	v_mfma_f32_32x32x16_bf16 v[114:129], v[166:169], v[134:137], v[114:129]
	s_waitcnt lgkmcnt(4)
	v_mfma_f32_32x32x16_bf16 v[98:113], v[162:165], v[134:137], v[98:113]
	s_waitcnt lgkmcnt(3)
	v_mfma_f32_32x32x16_bf16 v[114:129], v[158:161], v[138:141], v[114:129]
	s_waitcnt lgkmcnt(2)
	v_mfma_f32_32x32x16_bf16 v[98:113], v[154:157], v[138:141], v[98:113]
	s_waitcnt lgkmcnt(1)
	v_mfma_f32_32x32x16_bf16 v[114:129], v[150:153], v[142:145], v[114:129]
	s_waitcnt lgkmcnt(0)
	v_mfma_f32_32x32x16_bf16 v[98:113], v[146:149], v[142:145], v[98:113]
	v_pk_add_f32 v[146:147], v[66:67], v[82:83]
	v_pk_add_f32 v[148:149], v[68:69], v[84:85]
	v_pk_add_f32 v[150:151], v[70:71], v[86:87]
	v_pk_add_f32 v[152:153], v[72:73], v[88:89]
	v_pk_add_f32 v[154:155], v[74:75], v[90:91]
	v_pk_add_f32 v[156:157], v[76:77], v[92:93]
	v_pk_add_f32 v[158:159], v[78:79], v[94:95]
	v_pk_add_f32 v[160:161], v[80:81], v[96:97]
	v_pk_add_f32 v[146:147], v[146:147], v[148:149]
	v_pk_add_f32 v[150:151], v[150:151], v[152:153]
	v_pk_add_f32 v[154:155], v[154:155], v[156:157]
	v_pk_add_f32 v[158:159], v[158:159], v[160:161]
	v_pk_add_f32 v[146:147], v[146:147], v[150:151]
	v_pk_add_f32 v[154:155], v[154:155], v[158:159]
	v_cvt_pk_bf16_f32 v66, v66, v67
	v_cvt_pk_bf16_f32 v67, v68, v69
	v_cvt_pk_bf16_f32 v68, v70, v71
	v_cvt_pk_bf16_f32 v69, v72, v73
	v_pk_add_f32 v[146:147], v[146:147], v[154:155]
	v_cvt_pk_bf16_f32 v70, v74, v75
	v_cvt_pk_bf16_f32 v71, v76, v77
	v_cvt_pk_bf16_f32 v72, v78, v79
	v_cvt_pk_bf16_f32 v73, v80, v81
	v_cvt_pk_bf16_f32 v74, v82, v83
	v_cvt_pk_bf16_f32 v75, v84, v85
	v_cvt_pk_bf16_f32 v76, v86, v87
	v_cvt_pk_bf16_f32 v77, v88, v89
	v_cvt_pk_bf16_f32 v78, v90, v91
	v_cvt_pk_bf16_f32 v79, v92, v93
	v_cvt_pk_bf16_f32 v80, v94, v95
	v_cvt_pk_bf16_f32 v81, v96, v97
	v_add_f32_e32 v162, v146, v147
	s_nop 0
	v_add_f32_e32 v0, v162, v213
	ds_read_b128 v[82:85], v208 offset:32768
	ds_read_b128 v[86:89], v208 offset:36864
	ds_read_b128 v[90:93], v208 offset:40960
	ds_read_b128 v[94:97], v208 offset:45056
	ds_read_b128 v[146:149], v209 offset:32768
	ds_read_b128 v[150:153], v209 offset:36864
	ds_read_b128 v[154:157], v209 offset:40960
	ds_read_b128 v[158:161], v209 offset:45056
	s_add_i32 s14, s77, 0xffff0000
	s_and_b32 s14, s14, 0x3e0000
	s_lshl_b32 s22, s14, 1
	s_mov_b32 m0, s70
	v_lshl_add_u64 v[164:165], v[188:189], 0, s[22:23]
	global_load_lds_dwordx4 v[164:165], off
	v_lshl_add_u64 v[164:165], v[192:193], 0, s[22:23]
	s_mov_b32 m0, s29
	s_lshl_b32 s22, s80, 1
	global_load_lds_dwordx4 v[164:165], off
	v_lshl_add_u64 v[164:165], v[190:191], 0, s[22:23]
	s_add_i32 m0, s70, 0xc000
	global_load_lds_dwordx4 v[164:165], off
	v_lshl_add_u64 v[164:165], v[194:195], 0, s[22:23]
	s_add_i32 m0, s70, 0xc400
	s_nop 0
	global_load_lds_dwordx4 v[164:165], off
	s_waitcnt lgkmcnt(0)
	v_mfma_f32_32x32x16_bf16 v[50:65], v[66:69], v[82:85], v[50:65]
	ds_read_b128 v[82:85], v210 offset:32768
	v_exp_f32_e32 v114, v114
	v_exp_f32_e32 v115, v115
	v_mfma_f32_32x32x16_bf16 v[34:49], v[66:69], v[86:89], v[34:49]
	ds_read_b128 v[86:89], v210 offset:36864
	v_exp_f32_e32 v116, v116
	v_exp_f32_e32 v117, v117
	v_mfma_f32_32x32x16_bf16 v[18:33], v[66:69], v[90:93], v[18:33]
	ds_read_b128 v[90:93], v210 offset:40960
	v_exp_f32_e32 v118, v118
	v_exp_f32_e32 v119, v119
	v_mfma_f32_32x32x16_bf16 v[2:17], v[66:69], v[94:97], v[2:17]
	ds_read_b128 v[66:69], v210 offset:45056
	v_exp_f32_e32 v120, v120
	v_exp_f32_e32 v121, v121
	v_mfma_f32_32x32x16_bf16 v[50:65], v[70:73], v[146:149], v[50:65]
	ds_read_b128 v[94:97], v212 offset:32768
	v_exp_f32_e32 v122, v122
	v_exp_f32_e32 v123, v123
	v_mfma_f32_32x32x16_bf16 v[34:49], v[70:73], v[150:153], v[34:49]
	ds_read_b128 v[146:149], v212 offset:36864
	v_exp_f32_e32 v124, v124
	v_exp_f32_e32 v125, v125
	v_mfma_f32_32x32x16_bf16 v[18:33], v[70:73], v[154:157], v[18:33]
	ds_read_b128 v[150:153], v212 offset:40960
	v_exp_f32_e32 v126, v126
	v_exp_f32_e32 v127, v127
	v_mfma_f32_32x32x16_bf16 v[2:17], v[70:73], v[158:161], v[2:17]
	ds_read_b128 v[70:73], v212 offset:45056
	v_exp_f32_e32 v128, v128
	v_exp_f32_e32 v129, v129
	s_waitcnt lgkmcnt(0)
	v_mfma_f32_32x32x16_bf16 v[50:65], v[74:77], v[82:85], v[50:65]
	v_exp_f32_e32 v98, v98
	v_exp_f32_e32 v99, v99
	v_mfma_f32_32x32x16_bf16 v[34:49], v[74:77], v[86:89], v[34:49]
	v_exp_f32_e32 v100, v100
	v_exp_f32_e32 v101, v101
	v_mfma_f32_32x32x16_bf16 v[18:33], v[74:77], v[90:93], v[18:33]
	v_exp_f32_e32 v102, v102
	v_exp_f32_e32 v103, v103
	v_mfma_f32_32x32x16_bf16 v[2:17], v[74:77], v[66:69], v[2:17]
	v_exp_f32_e32 v104, v104
	v_exp_f32_e32 v105, v105
	v_mfma_f32_32x32x16_bf16 v[50:65], v[78:81], v[94:97], v[50:65]
	v_exp_f32_e32 v106, v106
	v_exp_f32_e32 v107, v107
	v_mfma_f32_32x32x16_bf16 v[34:49], v[78:81], v[146:149], v[34:49]
	v_exp_f32_e32 v108, v108
	v_exp_f32_e32 v109, v109
	v_mfma_f32_32x32x16_bf16 v[18:33], v[78:81], v[150:153], v[18:33]
	v_exp_f32_e32 v110, v110
	v_exp_f32_e32 v111, v111
	v_mfma_f32_32x32x16_bf16 v[2:17], v[78:81], v[70:73], v[2:17]
	v_exp_f32_e32 v112, v112
	v_exp_f32_e32 v113, v113
	s_and_b64 s[0:1], s[0:1], exec
	s_waitcnt vmcnt(0)
	s_cselect_b32 s14, 1, 2
	s_and_b64 s[0:1], s[40:41], exec
	s_cselect_b32 s14, s14, 0
	s_cmp_eq_u32 s14, s79
	s_waitcnt vmcnt(0)
	s_barrier
	s_cbranch_scc1 .LBB0_290
	s_cmp_eq_u32 s79, 0
	s_cselect_b64 vcc, -1, 0
	s_cmp_eq_u32 s79, 2
	s_cselect_b64 s[0:1], -1, 0
	v_cndmask_b32_e64 v66, 0, v201, s[0:1]
	s_cmp_eq_u32 s14, 2
	v_cndmask_b32_e32 v66, v66, v200, vcc
	s_cselect_b64 vcc, -1, 0
	v_cndmask_b32_e32 v67, 0, v201, vcc
	v_cndmask_b32_e64 v67, v200, v67, s[40:41]
	v_sub_f32_e32 v66, v66, v67
	v_exp_f32_e32 v66, v66
	s_nop 0
	v_pk_mul_f32 v[64:65], v[66:67], v[64:65] op_sel_hi:[0,1]
	v_pk_mul_f32 v[62:63], v[66:67], v[62:63] op_sel_hi:[0,1]
	v_pk_mul_f32 v[60:61], v[66:67], v[60:61] op_sel_hi:[0,1]
	v_pk_mul_f32 v[58:59], v[66:67], v[58:59] op_sel_hi:[0,1]
	v_pk_mul_f32 v[56:57], v[66:67], v[56:57] op_sel_hi:[0,1]
	v_pk_mul_f32 v[54:55], v[66:67], v[54:55] op_sel_hi:[0,1]
	v_pk_mul_f32 v[52:53], v[66:67], v[52:53] op_sel_hi:[0,1]
	v_pk_mul_f32 v[50:51], v[66:67], v[50:51] op_sel_hi:[0,1]
	v_pk_mul_f32 v[48:49], v[66:67], v[48:49] op_sel_hi:[0,1]
	v_pk_mul_f32 v[46:47], v[66:67], v[46:47] op_sel_hi:[0,1]
	v_pk_mul_f32 v[44:45], v[66:67], v[44:45] op_sel_hi:[0,1]
	v_pk_mul_f32 v[42:43], v[66:67], v[42:43] op_sel_hi:[0,1]
	v_pk_mul_f32 v[40:41], v[66:67], v[40:41] op_sel_hi:[0,1]
	v_pk_mul_f32 v[38:39], v[66:67], v[38:39] op_sel_hi:[0,1]
	v_pk_mul_f32 v[36:37], v[66:67], v[36:37] op_sel_hi:[0,1]
	v_pk_mul_f32 v[34:35], v[66:67], v[34:35] op_sel_hi:[0,1]
	v_pk_mul_f32 v[32:33], v[66:67], v[32:33] op_sel_hi:[0,1]
	v_pk_mul_f32 v[30:31], v[66:67], v[30:31] op_sel_hi:[0,1]
	v_pk_mul_f32 v[28:29], v[66:67], v[28:29] op_sel_hi:[0,1]
	v_pk_mul_f32 v[26:27], v[66:67], v[26:27] op_sel_hi:[0,1]
	v_pk_mul_f32 v[24:25], v[66:67], v[24:25] op_sel_hi:[0,1]
	v_pk_mul_f32 v[22:23], v[66:67], v[22:23] op_sel_hi:[0,1]
	v_pk_mul_f32 v[20:21], v[66:67], v[20:21] op_sel_hi:[0,1]
	v_pk_mul_f32 v[18:19], v[66:67], v[18:19] op_sel_hi:[0,1]
	v_pk_mul_f32 v[16:17], v[66:67], v[16:17] op_sel_hi:[0,1]
	v_pk_mul_f32 v[14:15], v[66:67], v[14:15] op_sel_hi:[0,1]
	v_pk_mul_f32 v[12:13], v[66:67], v[12:13] op_sel_hi:[0,1]
	v_pk_mul_f32 v[10:11], v[66:67], v[10:11] op_sel_hi:[0,1]
	v_pk_mul_f32 v[8:9], v[66:67], v[8:9] op_sel_hi:[0,1]
	v_pk_mul_f32 v[6:7], v[66:67], v[6:7] op_sel_hi:[0,1]
	v_pk_mul_f32 v[4:5], v[66:67], v[4:5] op_sel_hi:[0,1]
	v_pk_mul_f32 v[2:3], v[66:67], v[2:3] op_sel_hi:[0,1]
	v_mul_f32_e32 v0, v0, v66
	s_branch .LBB0_291
